# merge epilogue: gate loads of all 4 row-group batches issued together (one HBM round trip per unit)
# baseline (speedup 1.0000x reference)
.LBB0_1026:
	global_load_dwordx4 v[136:139], v[16:17], off offset:256
	s_mov_b32 s59, 0
	s_mov_b32 s58, 0x20000
	v_lshl_add_u64 v[252:253], v[16:17], 0, s[58:59]
	global_load_dwordx4 v[180:183], v[252:253], off
	global_load_dwordx4 v[184:187], v[252:253], off offset:256
	s_mov_b32 s58, 0x40000
	v_lshl_add_u64 v[244:245], v[16:17], 0, s[58:59]
	global_load_dwordx4 v[188:191], v[244:245], off
	global_load_dwordx4 v[192:195], v[244:245], off offset:256
	s_mov_b32 s58, 0xe0000
	v_lshl_add_u64 v[246:247], v[16:17], 0, s[58:59]
	global_load_dwordx4 v[196:199], v[246:247], off
	global_load_dwordx4 v[200:203], v[246:247], off offset:256
	s_mov_b32 s58, 0x100000
	v_lshl_add_u64 v[252:253], v[16:17], 0, s[58:59]
	global_load_dwordx4 v[204:207], v[252:253], off
	global_load_dwordx4 v[208:211], v[252:253], off offset:256
	s_mov_b32 s58, 0x120000
	v_lshl_add_u64 v[244:245], v[16:17], 0, s[58:59]
	global_load_dwordx4 v[222:225], v[244:245], off
	global_load_dwordx4 v[226:229], v[244:245], off offset:256
	s_mov_b32 s58, 0x140000
	v_lshl_add_u64 v[246:247], v[16:17], 0, s[58:59]
	global_load_dwordx4 v[234:237], v[246:247], off
	global_load_dwordx4 v[238:241], v[246:247], off offset:256
	s_and_b64 vcc, exec, s[4:5]
	v_mov_b32_e32 v248, 0x260
	s_cbranch_vccnz .LBB0_1028
	global_load_dwordx4 v[16:19], v[170:171], off offset:256

.LBB0_1036:
	v_cvt_pk_bf16_f32 v116, v116, v117
	v_cvt_pk_bf16_f32 v117, v118, v119
	v_cvt_pk_bf16_f32 v118, v112, v113
	v_add3_u32 v112, s13, v176, 32
	v_ashrrev_i32_e32 v113, 31, v112
	v_cvt_pk_bf16_f32 v119, v114, v115
	v_lshlrev_b64 v[114:115], 13, v[112:113]
	global_store_dwordx4 v[170:171], v[116:119], off offset:256
	v_lshl_add_u64 v[114:115], s[20:21], 0, v[114:115]
	v_lshl_add_u64 v[114:115], v[166:167], 1, v[114:115]
	v_lshlrev_b64 v[116:117], 11, v[112:113]
	v_lshl_add_u64 v[116:117], s[8:9], 0, v[116:117]
	s_and_b64 vcc, exec, s[4:5]
	v_lshl_add_u64 v[128:129], v[166:167], 1, v[116:117]
	s_cbranch_vccnz .LBB0_1038
	global_load_dwordx4 v[44:47], v[128:129], off
.LBB0_1038:
	s_and_b64 vcc, exec, s[4:5]
	s_cbranch_vccnz .LBB0_1040
	global_load_dwordx4 v[32:35], v[128:129], off offset:256
.LBB0_1040:
	v_or_b32_e32 v114, 16, v112
	v_ashrrev_i32_e32 v115, 31, v114
	v_lshlrev_b64 v[112:113], 13, v[114:115]
	v_lshl_add_u64 v[112:113], s[20:21], 0, v[112:113]
	v_lshl_add_u64 v[112:113], v[166:167], 1, v[112:113]
	v_lshlrev_b64 v[114:115], 11, v[114:115]
	v_lshl_add_u64 v[114:115], s[8:9], 0, v[114:115]
	s_and_b64 vcc, exec, s[4:5]
	v_lshl_add_u64 v[130:131], v[166:167], 1, v[114:115]
	s_cbranch_vccnz .LBB0_1042
	global_load_dwordx4 v[24:27], v[130:131], off
.LBB0_1042:
	s_nop 0
	s_and_b64 vcc, exec, s[4:5]
	s_cbranch_vccnz .LBB0_1044
	global_load_dwordx4 v[16:19], v[130:131], off offset:256
.LBB0_1044:
	s_waitcnt vmcnt(0) lgkmcnt(0)
	v_lshlrev_b32_e32 v130, 16, v180
	v_and_b32_e32 v131, 0xffff0000, v180
	v_lshlrev_b32_e32 v124, 16, v181
	v_and_b32_e32 v125, 0xffff0000, v181
	v_pk_mul_f32 v[110:111], v[110:111], v[124:125]
	v_lshlrev_b32_e32 v124, 16, v182
	v_and_b32_e32 v125, 0xffff0000, v182
	v_pk_mul_f32 v[104:105], v[104:105], v[124:125]
	v_lshlrev_b32_e32 v124, 16, v183
	v_and_b32_e32 v125, 0xffff0000, v183
	v_pk_mul_f32 v[108:109], v[108:109], v[130:131]
	s_and_b64 vcc, exec, s[4:5]
	v_pk_mul_f32 v[106:107], v[106:107], v[124:125]
	s_cbranch_vccnz .LBB0_1046
	v_lshlrev_b32_e32 v124, 16, v44
	v_and_b32_e32 v125, 0xffff0000, v44
	v_pk_add_f32 v[108:109], v[108:109], v[124:125]
	v_lshlrev_b32_e32 v124, 16, v45
	v_and_b32_e32 v125, 0xffff0000, v45
	v_pk_add_f32 v[110:111], v[110:111], v[124:125]
	v_lshlrev_b32_e32 v124, 16, v46
	v_and_b32_e32 v125, 0xffff0000, v46
	v_pk_add_f32 v[104:105], v[104:105], v[124:125]
	v_lshlrev_b32_e32 v124, 16, v47
	v_and_b32_e32 v125, 0xffff0000, v47
	v_pk_add_f32 v[106:107], v[106:107], v[124:125]
.LBB0_1046:
	v_cvt_pk_bf16_f32 v108, v108, v109
	v_cvt_pk_bf16_f32 v109, v110, v111
	v_cvt_pk_bf16_f32 v110, v104, v105
	v_lshlrev_b32_e32 v104, 16, v184
	v_and_b32_e32 v105, 0xffff0000, v184
	v_pk_mul_f32 v[100:101], v[100:101], v[104:105]
	v_lshlrev_b32_e32 v104, 16, v185
	v_and_b32_e32 v105, 0xffff0000, v185
	v_pk_mul_f32 v[102:103], v[102:103], v[104:105]
	v_lshlrev_b32_e32 v104, 16, v186
	v_and_b32_e32 v105, 0xffff0000, v186
	v_pk_mul_f32 v[96:97], v[96:97], v[104:105]
	v_lshlrev_b32_e32 v104, 16, v187
	v_and_b32_e32 v105, 0xffff0000, v187
	v_cvt_pk_bf16_f32 v111, v106, v107
	s_and_b64 vcc, exec, s[4:5]
	v_pk_mul_f32 v[98:99], v[98:99], v[104:105]
	global_store_dwordx4 v[128:129], v[108:111], off
	s_cbranch_vccnz .LBB0_1048
	v_lshlrev_b32_e32 v104, 16, v32
	v_and_b32_e32 v105, 0xffff0000, v32
	v_pk_add_f32 v[100:101], v[100:101], v[104:105]
	v_lshlrev_b32_e32 v104, 16, v33
	v_and_b32_e32 v105, 0xffff0000, v33
	v_pk_add_f32 v[102:103], v[102:103], v[104:105]
	v_lshlrev_b32_e32 v104, 16, v34
	v_and_b32_e32 v105, 0xffff0000, v34
	v_pk_add_f32 v[96:97], v[96:97], v[104:105]
	v_lshlrev_b32_e32 v104, 16, v35
	v_and_b32_e32 v105, 0xffff0000, v35
	v_pk_add_f32 v[98:99], v[98:99], v[104:105]
.LBB0_1048:
	v_cvt_pk_bf16_f32 v100, v100, v101
	v_cvt_pk_bf16_f32 v101, v102, v103
	v_cvt_pk_bf16_f32 v102, v96, v97
	v_lshlrev_b32_e32 v96, 16, v188
	v_and_b32_e32 v97, 0xffff0000, v188
	v_pk_mul_f32 v[92:93], v[92:93], v[96:97]
	v_lshlrev_b32_e32 v96, 16, v189
	v_and_b32_e32 v97, 0xffff0000, v189
	v_pk_mul_f32 v[94:95], v[94:95], v[96:97]
	v_lshlrev_b32_e32 v96, 16, v190
	v_and_b32_e32 v97, 0xffff0000, v190
	v_pk_mul_f32 v[88:89], v[88:89], v[96:97]
	v_lshlrev_b32_e32 v96, 16, v191
	v_and_b32_e32 v97, 0xffff0000, v191
	v_cvt_pk_bf16_f32 v103, v98, v99
	s_and_b64 vcc, exec, s[4:5]
	v_pk_mul_f32 v[90:91], v[90:91], v[96:97]
	global_store_dwordx4 v[128:129], v[100:103], off offset:256
	s_cbranch_vccnz .LBB0_1050
	v_lshlrev_b32_e32 v96, 16, v24
	v_and_b32_e32 v97, 0xffff0000, v24
	v_pk_add_f32 v[92:93], v[92:93], v[96:97]
	v_lshlrev_b32_e32 v96, 16, v25
	v_and_b32_e32 v97, 0xffff0000, v25
	v_pk_add_f32 v[94:95], v[94:95], v[96:97]
	v_lshlrev_b32_e32 v96, 16, v26
	v_and_b32_e32 v97, 0xffff0000, v26
	v_pk_add_f32 v[88:89], v[88:89], v[96:97]
	v_lshlrev_b32_e32 v96, 16, v27
	v_and_b32_e32 v97, 0xffff0000, v27
	v_pk_add_f32 v[90:91], v[90:91], v[96:97]
.LBB0_1050:
	v_or_b32_e32 v96, 48, v168
	v_cvt_pk_bf16_f32 v92, v92, v93
	v_cvt_pk_bf16_f32 v93, v94, v95
	v_cvt_pk_bf16_f32 v95, v90, v91
	v_lshlrev_b32_e32 v90, 16, v192
	v_and_b32_e32 v91, 0xffff0000, v192
	v_ashrrev_i32_e32 v97, 31, v96
	v_pk_mul_f32 v[84:85], v[84:85], v[90:91]
	v_lshlrev_b32_e32 v90, 16, v193
	v_and_b32_e32 v91, 0xffff0000, v193
	v_cvt_pk_bf16_f32 v94, v88, v89
	v_lshlrev_b64 v[88:89], 11, v[96:97]
	v_pk_mul_f32 v[86:87], v[86:87], v[90:91]
	v_lshlrev_b32_e32 v90, 16, v194
	v_and_b32_e32 v91, 0xffff0000, v194
	v_lshl_add_u64 v[88:89], s[8:9], 0, v[88:89]
	v_pk_mul_f32 v[80:81], v[80:81], v[90:91]
	v_lshlrev_b32_e32 v90, 16, v195
	v_and_b32_e32 v91, 0xffff0000, v195
	v_lshl_add_u64 v[88:89], v[166:167], 1, v[88:89]
	s_and_b64 vcc, exec, s[4:5]
	v_pk_mul_f32 v[82:83], v[82:83], v[90:91]
	global_store_dwordx4 v[88:89], v[92:95], off
	s_cbranch_vccnz .LBB0_1052
	v_lshlrev_b32_e32 v90, 16, v16
	v_and_b32_e32 v91, 0xffff0000, v16
	v_pk_add_f32 v[84:85], v[84:85], v[90:91]
	v_lshlrev_b32_e32 v90, 16, v17
	v_and_b32_e32 v91, 0xffff0000, v17
	v_pk_add_f32 v[86:87], v[86:87], v[90:91]
	v_lshlrev_b32_e32 v90, 16, v18
	v_and_b32_e32 v91, 0xffff0000, v18
	v_pk_add_f32 v[80:81], v[80:81], v[90:91]
	v_lshlrev_b32_e32 v90, 16, v19
	v_and_b32_e32 v91, 0xffff0000, v19
	v_pk_add_f32 v[82:83], v[82:83], v[90:91]
.LBB0_1052:
	v_cvt_pk_bf16_f32 v84, v84, v85
	v_cvt_pk_bf16_f32 v85, v86, v87
	v_cvt_pk_bf16_f32 v86, v80, v81
	v_add_u32_e32 v80, 0x80, v168
	v_ashrrev_i32_e32 v81, 31, v80
	v_cvt_pk_bf16_f32 v87, v82, v83
	v_lshlrev_b64 v[82:83], 13, v[80:81]
	global_store_dwordx4 v[88:89], v[84:87], off offset:256
	v_lshl_add_u64 v[82:83], s[20:21], 0, v[82:83]
	v_lshl_add_u64 v[82:83], v[166:167], 1, v[82:83]
	v_lshlrev_b64 v[84:85], 11, v[80:81]
	v_lshl_add_u64 v[84:85], s[8:9], 0, v[84:85]
	s_and_b64 vcc, exec, s[4:5]
	v_lshl_add_u64 v[96:97], v[166:167], 1, v[84:85]
	s_cbranch_vccnz .LBB0_1054
	global_load_dwordx4 v[44:47], v[96:97], off
.LBB0_1054:
	s_and_b64 vcc, exec, s[4:5]
	s_cbranch_vccnz .LBB0_1056
	global_load_dwordx4 v[32:35], v[96:97], off offset:256
.LBB0_1056:
	v_or_b32_e32 v82, 16, v80
	v_ashrrev_i32_e32 v83, 31, v82
	v_lshlrev_b64 v[80:81], 13, v[82:83]
	v_lshl_add_u64 v[80:81], s[20:21], 0, v[80:81]
	v_lshl_add_u64 v[80:81], v[166:167], 1, v[80:81]
	v_lshlrev_b64 v[82:83], 11, v[82:83]
	v_lshl_add_u64 v[82:83], s[8:9], 0, v[82:83]
	s_and_b64 vcc, exec, s[4:5]
	v_lshl_add_u64 v[98:99], v[166:167], 1, v[82:83]
	s_cbranch_vccnz .LBB0_1058
	global_load_dwordx4 v[24:27], v[98:99], off
.LBB0_1058:
	s_nop 0
	s_and_b64 vcc, exec, s[4:5]
	s_cbranch_vccnz .LBB0_1060
	global_load_dwordx4 v[16:19], v[98:99], off offset:256
.LBB0_1060:
	s_waitcnt vmcnt(0) lgkmcnt(0)
	v_lshlrev_b32_e32 v98, 16, v196
	v_and_b32_e32 v99, 0xffff0000, v196
	v_lshlrev_b32_e32 v92, 16, v197
	v_and_b32_e32 v93, 0xffff0000, v197
	v_pk_mul_f32 v[78:79], v[78:79], v[92:93]
	v_lshlrev_b32_e32 v92, 16, v198
	v_and_b32_e32 v93, 0xffff0000, v198
	v_pk_mul_f32 v[72:73], v[72:73], v[92:93]
	v_lshlrev_b32_e32 v92, 16, v199
	v_and_b32_e32 v93, 0xffff0000, v199
	v_pk_mul_f32 v[76:77], v[76:77], v[98:99]
	s_and_b64 vcc, exec, s[4:5]
	v_pk_mul_f32 v[74:75], v[74:75], v[92:93]
	s_cbranch_vccnz .LBB0_1062
	v_lshlrev_b32_e32 v92, 16, v44
	v_and_b32_e32 v93, 0xffff0000, v44
	v_pk_add_f32 v[76:77], v[76:77], v[92:93]
	v_lshlrev_b32_e32 v92, 16, v45
	v_and_b32_e32 v93, 0xffff0000, v45
	v_pk_add_f32 v[78:79], v[78:79], v[92:93]
	v_lshlrev_b32_e32 v92, 16, v46
	v_and_b32_e32 v93, 0xffff0000, v46
	v_pk_add_f32 v[72:73], v[72:73], v[92:93]
	v_lshlrev_b32_e32 v92, 16, v47
	v_and_b32_e32 v93, 0xffff0000, v47
	v_pk_add_f32 v[74:75], v[74:75], v[92:93]
.LBB0_1062:
	v_cvt_pk_bf16_f32 v76, v76, v77
	v_cvt_pk_bf16_f32 v77, v78, v79
	v_cvt_pk_bf16_f32 v78, v72, v73
	v_lshlrev_b32_e32 v72, 16, v200
	v_and_b32_e32 v73, 0xffff0000, v200
	v_pk_mul_f32 v[68:69], v[68:69], v[72:73]
	v_lshlrev_b32_e32 v72, 16, v201
	v_and_b32_e32 v73, 0xffff0000, v201
	v_pk_mul_f32 v[70:71], v[70:71], v[72:73]
	v_lshlrev_b32_e32 v72, 16, v202
	v_and_b32_e32 v73, 0xffff0000, v202
	v_pk_mul_f32 v[64:65], v[64:65], v[72:73]
	v_lshlrev_b32_e32 v72, 16, v203
	v_and_b32_e32 v73, 0xffff0000, v203
	v_cvt_pk_bf16_f32 v79, v74, v75
	s_and_b64 vcc, exec, s[4:5]
	v_pk_mul_f32 v[66:67], v[66:67], v[72:73]
	global_store_dwordx4 v[96:97], v[76:79], off
	s_cbranch_vccnz .LBB0_1064
	v_lshlrev_b32_e32 v72, 16, v32
	v_and_b32_e32 v73, 0xffff0000, v32
	v_pk_add_f32 v[68:69], v[68:69], v[72:73]
	v_lshlrev_b32_e32 v72, 16, v33
	v_and_b32_e32 v73, 0xffff0000, v33
	v_pk_add_f32 v[70:71], v[70:71], v[72:73]
	v_lshlrev_b32_e32 v72, 16, v34
	v_and_b32_e32 v73, 0xffff0000, v34
	v_pk_add_f32 v[64:65], v[64:65], v[72:73]
	v_lshlrev_b32_e32 v72, 16, v35
	v_and_b32_e32 v73, 0xffff0000, v35
	v_pk_add_f32 v[66:67], v[66:67], v[72:73]
.LBB0_1064:
	v_cvt_pk_bf16_f32 v68, v68, v69
	v_cvt_pk_bf16_f32 v69, v70, v71
	v_cvt_pk_bf16_f32 v70, v64, v65
	v_lshlrev_b32_e32 v64, 16, v204
	v_and_b32_e32 v65, 0xffff0000, v204
	v_pk_mul_f32 v[60:61], v[60:61], v[64:65]
	v_lshlrev_b32_e32 v64, 16, v205
	v_and_b32_e32 v65, 0xffff0000, v205
	v_pk_mul_f32 v[62:63], v[62:63], v[64:65]
	v_lshlrev_b32_e32 v64, 16, v206
	v_and_b32_e32 v65, 0xffff0000, v206
	v_pk_mul_f32 v[56:57], v[56:57], v[64:65]
	v_lshlrev_b32_e32 v64, 16, v207
	v_and_b32_e32 v65, 0xffff0000, v207
	v_cvt_pk_bf16_f32 v71, v66, v67
	s_and_b64 vcc, exec, s[4:5]
	v_pk_mul_f32 v[58:59], v[58:59], v[64:65]
	global_store_dwordx4 v[96:97], v[68:71], off offset:256
	s_cbranch_vccnz .LBB0_1066
	v_lshlrev_b32_e32 v64, 16, v24
	v_and_b32_e32 v65, 0xffff0000, v24
	v_pk_add_f32 v[60:61], v[60:61], v[64:65]
	v_lshlrev_b32_e32 v64, 16, v25
	v_and_b32_e32 v65, 0xffff0000, v25
	v_pk_add_f32 v[62:63], v[62:63], v[64:65]
	v_lshlrev_b32_e32 v64, 16, v26
	v_and_b32_e32 v65, 0xffff0000, v26
	v_pk_add_f32 v[56:57], v[56:57], v[64:65]
	v_lshlrev_b32_e32 v64, 16, v27
	v_and_b32_e32 v65, 0xffff0000, v27
	v_pk_add_f32 v[58:59], v[58:59], v[64:65]
.LBB0_1066:
	v_add_u32_e32 v64, 0x90, v168
	v_cvt_pk_bf16_f32 v60, v60, v61
	v_cvt_pk_bf16_f32 v61, v62, v63
	v_cvt_pk_bf16_f32 v63, v58, v59
	v_lshlrev_b32_e32 v58, 16, v208
	v_and_b32_e32 v59, 0xffff0000, v208
	v_ashrrev_i32_e32 v65, 31, v64
	v_pk_mul_f32 v[52:53], v[52:53], v[58:59]
	v_lshlrev_b32_e32 v58, 16, v209
	v_and_b32_e32 v59, 0xffff0000, v209
	v_cvt_pk_bf16_f32 v62, v56, v57
	v_lshlrev_b64 v[56:57], 11, v[64:65]
	v_pk_mul_f32 v[54:55], v[54:55], v[58:59]
	v_lshlrev_b32_e32 v58, 16, v210
	v_and_b32_e32 v59, 0xffff0000, v210
	v_lshl_add_u64 v[56:57], s[8:9], 0, v[56:57]
	v_pk_mul_f32 v[48:49], v[48:49], v[58:59]
	v_lshlrev_b32_e32 v58, 16, v211
	v_and_b32_e32 v59, 0xffff0000, v211
	v_lshl_add_u64 v[56:57], v[166:167], 1, v[56:57]
	s_and_b64 vcc, exec, s[4:5]
	v_pk_mul_f32 v[50:51], v[50:51], v[58:59]
	global_store_dwordx4 v[56:57], v[60:63], off
	s_cbranch_vccnz .LBB0_1068
	v_lshlrev_b32_e32 v58, 16, v16
	v_and_b32_e32 v59, 0xffff0000, v16
	v_pk_add_f32 v[52:53], v[52:53], v[58:59]
	v_lshlrev_b32_e32 v58, 16, v17
	v_and_b32_e32 v59, 0xffff0000, v17
	v_pk_add_f32 v[54:55], v[54:55], v[58:59]
	v_lshlrev_b32_e32 v58, 16, v18
	v_and_b32_e32 v59, 0xffff0000, v18
	v_pk_add_f32 v[48:49], v[48:49], v[58:59]
	v_lshlrev_b32_e32 v58, 16, v19
	v_and_b32_e32 v59, 0xffff0000, v19
	v_pk_add_f32 v[50:51], v[50:51], v[58:59]
.LBB0_1068:
	v_cvt_pk_bf16_f32 v52, v52, v53
	v_cvt_pk_bf16_f32 v53, v54, v55
	v_cvt_pk_bf16_f32 v54, v48, v49
	v_add_u32_e32 v48, 0xa0, v168
	v_ashrrev_i32_e32 v49, 31, v48
	v_cvt_pk_bf16_f32 v55, v50, v51
	v_lshlrev_b64 v[50:51], 13, v[48:49]
	global_store_dwordx4 v[56:57], v[52:55], off offset:256
	v_lshl_add_u64 v[50:51], s[20:21], 0, v[50:51]
	v_lshl_add_u64 v[50:51], v[166:167], 1, v[50:51]
	v_lshlrev_b64 v[52:53], 11, v[48:49]
	v_lshl_add_u64 v[52:53], s[8:9], 0, v[52:53]
	s_and_b64 vcc, exec, s[4:5]
	v_lshl_add_u64 v[64:65], v[166:167], 1, v[52:53]
	s_cbranch_vccnz .LBB0_1070
	global_load_dwordx4 v[44:47], v[64:65], off
.LBB0_1070:
	s_and_b64 vcc, exec, s[4:5]
	s_cbranch_vccnz .LBB0_1072
	global_load_dwordx4 v[32:35], v[64:65], off offset:256
.LBB0_1072:
	v_or_b32_e32 v50, 16, v48
	v_ashrrev_i32_e32 v51, 31, v50
	v_lshlrev_b64 v[48:49], 13, v[50:51]
	v_lshl_add_u64 v[48:49], s[20:21], 0, v[48:49]
	v_lshl_add_u64 v[48:49], v[166:167], 1, v[48:49]
	v_lshlrev_b64 v[50:51], 11, v[50:51]
	v_lshl_add_u64 v[50:51], s[8:9], 0, v[50:51]
	s_and_b64 vcc, exec, s[4:5]
	v_lshl_add_u64 v[66:67], v[166:167], 1, v[50:51]
	s_cbranch_vccnz .LBB0_1074
	global_load_dwordx4 v[24:27], v[66:67], off
.LBB0_1074:
	s_nop 0
	s_and_b64 vcc, exec, s[4:5]
	s_cbranch_vccnz .LBB0_1076
	global_load_dwordx4 v[16:19], v[66:67], off offset:256
.LBB0_1076:
	s_waitcnt vmcnt(0) lgkmcnt(0)
	v_lshlrev_b32_e32 v66, 16, v222
	v_and_b32_e32 v67, 0xffff0000, v222
	v_lshlrev_b32_e32 v60, 16, v223
	v_and_b32_e32 v61, 0xffff0000, v223
	v_pk_mul_f32 v[42:43], v[42:43], v[60:61]
	v_lshlrev_b32_e32 v60, 16, v224
	v_and_b32_e32 v61, 0xffff0000, v224
	v_pk_mul_f32 v[36:37], v[36:37], v[60:61]
	v_lshlrev_b32_e32 v60, 16, v225
	v_and_b32_e32 v61, 0xffff0000, v225
	v_pk_mul_f32 v[40:41], v[40:41], v[66:67]
	s_and_b64 vcc, exec, s[4:5]
	v_pk_mul_f32 v[38:39], v[38:39], v[60:61]
	s_cbranch_vccnz .LBB0_1078
	v_lshlrev_b32_e32 v60, 16, v44
	v_and_b32_e32 v61, 0xffff0000, v44
	v_lshlrev_b32_e32 v44, 16, v45
	v_and_b32_e32 v45, 0xffff0000, v45
	v_pk_add_f32 v[42:43], v[42:43], v[44:45]
	v_lshlrev_b32_e32 v44, 16, v46
	v_and_b32_e32 v45, 0xffff0000, v46
	v_pk_add_f32 v[36:37], v[36:37], v[44:45]
	v_lshlrev_b32_e32 v44, 16, v47
	v_and_b32_e32 v45, 0xffff0000, v47
	v_pk_add_f32 v[40:41], v[40:41], v[60:61]
	v_pk_add_f32 v[38:39], v[38:39], v[44:45]
.LBB0_1078:
	v_cvt_pk_bf16_f32 v40, v40, v41
	v_cvt_pk_bf16_f32 v41, v42, v43
	v_cvt_pk_bf16_f32 v42, v36, v37
	v_lshlrev_b32_e32 v36, 16, v226
	v_and_b32_e32 v37, 0xffff0000, v226
	v_pk_mul_f32 v[28:29], v[28:29], v[36:37]
	v_lshlrev_b32_e32 v36, 16, v227
	v_and_b32_e32 v37, 0xffff0000, v227
	v_pk_mul_f32 v[30:31], v[30:31], v[36:37]
	v_lshlrev_b32_e32 v36, 16, v228
	v_and_b32_e32 v37, 0xffff0000, v228
	v_pk_mul_f32 v[20:21], v[20:21], v[36:37]
	v_lshlrev_b32_e32 v36, 16, v229
	v_and_b32_e32 v37, 0xffff0000, v229
	v_cvt_pk_bf16_f32 v43, v38, v39
	s_and_b64 vcc, exec, s[4:5]
	v_pk_mul_f32 v[22:23], v[22:23], v[36:37]
	global_store_dwordx4 v[64:65], v[40:43], off
	s_cbranch_vccnz .LBB0_1080
	v_lshlrev_b32_e32 v36, 16, v32
	v_and_b32_e32 v37, 0xffff0000, v32
	v_lshlrev_b32_e32 v32, 16, v33
	v_and_b32_e32 v33, 0xffff0000, v33
	v_pk_add_f32 v[30:31], v[30:31], v[32:33]
	v_lshlrev_b32_e32 v32, 16, v34
	v_and_b32_e32 v33, 0xffff0000, v34
	v_pk_add_f32 v[20:21], v[20:21], v[32:33]
	v_lshlrev_b32_e32 v32, 16, v35
	v_and_b32_e32 v33, 0xffff0000, v35
	v_pk_add_f32 v[28:29], v[28:29], v[36:37]
	v_pk_add_f32 v[22:23], v[22:23], v[32:33]
.LBB0_1080:
	v_cvt_pk_bf16_f32 v28, v28, v29
	v_cvt_pk_bf16_f32 v29, v30, v31
	v_cvt_pk_bf16_f32 v30, v20, v21
	v_lshlrev_b32_e32 v20, 16, v234
	v_and_b32_e32 v21, 0xffff0000, v234
	v_pk_mul_f32 v[12:13], v[12:13], v[20:21]
	v_lshlrev_b32_e32 v20, 16, v235
	v_and_b32_e32 v21, 0xffff0000, v235
	v_pk_mul_f32 v[14:15], v[14:15], v[20:21]
	v_lshlrev_b32_e32 v20, 16, v236
	v_and_b32_e32 v21, 0xffff0000, v236
	v_pk_mul_f32 v[8:9], v[8:9], v[20:21]
	v_lshlrev_b32_e32 v20, 16, v237
	v_and_b32_e32 v21, 0xffff0000, v237
	v_cvt_pk_bf16_f32 v31, v22, v23
	s_and_b64 vcc, exec, s[4:5]
	v_pk_mul_f32 v[10:11], v[10:11], v[20:21]
	global_store_dwordx4 v[64:65], v[28:31], off offset:256
	s_cbranch_vccnz .LBB0_1082
	v_lshlrev_b32_e32 v20, 16, v24
	v_and_b32_e32 v21, 0xffff0000, v24
	v_pk_add_f32 v[12:13], v[12:13], v[20:21]
	v_lshlrev_b32_e32 v20, 16, v25
	v_and_b32_e32 v21, 0xffff0000, v25
	v_pk_add_f32 v[14:15], v[14:15], v[20:21]
	v_lshlrev_b32_e32 v20, 16, v26
	v_and_b32_e32 v21, 0xffff0000, v26
	v_pk_add_f32 v[8:9], v[8:9], v[20:21]
	v_lshlrev_b32_e32 v20, 16, v27
	v_and_b32_e32 v21, 0xffff0000, v27
	v_pk_add_f32 v[10:11], v[10:11], v[20:21]
.LBB0_1082:
	v_add_u32_e32 v20, 0xb0, v168
	v_cvt_pk_bf16_f32 v12, v12, v13
	v_cvt_pk_bf16_f32 v13, v14, v15
	v_cvt_pk_bf16_f32 v15, v10, v11
	v_lshlrev_b32_e32 v10, 16, v238
	v_and_b32_e32 v11, 0xffff0000, v238
	v_ashrrev_i32_e32 v21, 31, v20
	v_pk_mul_f32 v[4:5], v[4:5], v[10:11]
	v_lshlrev_b32_e32 v10, 16, v239
	v_and_b32_e32 v11, 0xffff0000, v239
	v_cvt_pk_bf16_f32 v14, v8, v9
	v_lshlrev_b64 v[8:9], 11, v[20:21]
	v_pk_mul_f32 v[6:7], v[6:7], v[10:11]
	v_lshlrev_b32_e32 v10, 16, v240
	v_and_b32_e32 v11, 0xffff0000, v240
	v_lshl_add_u64 v[8:9], s[8:9], 0, v[8:9]
	v_pk_mul_f32 v[0:1], v[0:1], v[10:11]
	v_lshlrev_b32_e32 v10, 16, v241
	v_and_b32_e32 v11, 0xffff0000, v241
	v_lshl_add_u64 v[8:9], v[166:167], 1, v[8:9]
	s_and_b64 vcc, exec, s[4:5]
	v_pk_mul_f32 v[2:3], v[2:3], v[10:11]
	global_store_dwordx4 v[8:9], v[12:15], off
	s_cbranch_vccnz .LBB0_1084
	v_lshlrev_b32_e32 v10, 16, v16
	v_and_b32_e32 v11, 0xffff0000, v16
	v_pk_add_f32 v[4:5], v[4:5], v[10:11]
	v_lshlrev_b32_e32 v10, 16, v17
	v_and_b32_e32 v11, 0xffff0000, v17
	v_pk_add_f32 v[6:7], v[6:7], v[10:11]
	v_lshlrev_b32_e32 v10, 16, v18
	v_and_b32_e32 v11, 0xffff0000, v18
	v_pk_add_f32 v[0:1], v[0:1], v[10:11]
	v_lshlrev_b32_e32 v10, 16, v19
	v_and_b32_e32 v11, 0xffff0000, v19
	v_pk_add_f32 v[2:3], v[2:3], v[10:11]
